# phases G, I, F(second): epilogue loads as a sliding window with counted vmcnt waits instead of one load per vmcnt(0)
# speedup vs baseline: 1.0045x; 1.0025x over previous
; DI uint2 pk4(float a, float b, float c, float d) { uint2 o; o.x = pk2(a, b); o.y = pk2(c, d); return o; }
; DI void phaseF(int wv0, PP p, unsigned char* smem) {
;     ...
;     gemm256(wv0, acc, NSA + (size_t)brow * 512, 512, (const u16*)(p->ws + OFF_WAT) + (size_t)bcol * 512, 512, 512, smem);
;     epi256(wv0, acc, brow, bcol, [&](int ai, int bj, int m, int n, int row, int col0, f32x4& v) {
;       const unsigned og = (unsigned)row * 2048u + (unsigned)col0, om = (unsigned)row * 1024u + (unsigned)col0;
;       const uint2 t = *(const uint2*)(MR + om);
;       const uint2 gq = *(const uint2*)(MG + og);
;       *(uint2*)(MR + om) =
;           pk4(__uint_as_float(gq.x << 16) * v[0] + __uint_as_float(t.x << 16), __uint_as_float(gq.x & 0xffff0000u) * v[1] + __uint_as_float(t.x & 0xffff0000u),
;               __uint_as_float(gq.y << 16) * v[2] + __uint_as_float(t.y << 16), __uint_as_float(gq.y & 0xffff0000u) * v[3] + __uint_as_float(t.y & 0xffff0000u));
;     });
.LBB0_980:
	s_lshl_b32 s0, s94, 8
	v_and_or_b32 v132, v148, 15, s95
	v_lshrrev_b32_e32 v128, 2, v148
	v_and_or_b32 v128, v128, 12, s0
	v_or_b32_e32 v131, s81, v128
	v_lshlrev_b32_e32 v133, 12, v132
	v_lshl_add_u32 v224, v131, 1, v133
	v_lshlrev_b32_e32 v133, 11, v132
	v_lshl_add_u32 v232, v131, 1, v133
	v_add_u32_e32 v225, 0x10000, v224
	v_add_u32_e32 v233, 0x8000, v232
	v_add_u32_e32 v226, 0x20000, v224
	v_add_u32_e32 v234, 0x10000, v232
	v_add_u32_e32 v227, 0x30000, v224
	v_add_u32_e32 v235, 0x18000, v232
	v_add_u32_e32 v228, 0x80000, v224
	v_add_u32_e32 v236, 0x40000, v232
	v_add_u32_e32 v229, 0x90000, v224
	v_add_u32_e32 v237, 0x48000, v232
	v_add_u32_e32 v230, 0xa0000, v224
	v_add_u32_e32 v238, 0x50000, v232
	v_add_u32_e32 v231, 0xb0000, v224
	v_add_u32_e32 v239, 0x58000, v232
	global_load_dwordx2 v[160:161], v224, s[12:13] offset:0
	global_load_dwordx2 v[162:163], v232, s[14:15] offset:0
	global_load_dwordx2 v[164:165], v224, s[12:13] offset:32
	global_load_dwordx2 v[166:167], v232, s[14:15] offset:32
	global_load_dwordx2 v[168:169], v225, s[12:13] offset:0
	global_load_dwordx2 v[170:171], v233, s[14:15] offset:0
	global_load_dwordx2 v[172:173], v225, s[12:13] offset:32
	global_load_dwordx2 v[174:175], v233, s[14:15] offset:32
	global_load_dwordx2 v[176:177], v226, s[12:13] offset:0
	global_load_dwordx2 v[178:179], v234, s[14:15] offset:0
	global_load_dwordx2 v[180:181], v226, s[12:13] offset:32
	global_load_dwordx2 v[182:183], v234, s[14:15] offset:32
	global_load_dwordx2 v[184:185], v227, s[12:13] offset:0
	global_load_dwordx2 v[186:187], v235, s[14:15] offset:0
	global_load_dwordx2 v[188:189], v227, s[12:13] offset:32
	global_load_dwordx2 v[190:191], v235, s[14:15] offset:32
	global_load_dwordx2 v[192:193], v224, s[12:13] offset:256
	global_load_dwordx2 v[194:195], v232, s[14:15] offset:256
	global_load_dwordx2 v[196:197], v224, s[12:13] offset:288
	global_load_dwordx2 v[198:199], v232, s[14:15] offset:288
	global_load_dwordx2 v[200:201], v225, s[12:13] offset:256
	global_load_dwordx2 v[202:203], v233, s[14:15] offset:256
	global_load_dwordx2 v[204:205], v225, s[12:13] offset:288
	global_load_dwordx2 v[206:207], v233, s[14:15] offset:288
	global_load_dwordx2 v[208:209], v226, s[12:13] offset:256
	global_load_dwordx2 v[210:211], v234, s[14:15] offset:256
	global_load_dwordx2 v[212:213], v226, s[12:13] offset:288
	global_load_dwordx2 v[214:215], v234, s[14:15] offset:288
	global_load_dwordx2 v[216:217], v227, s[12:13] offset:256
	global_load_dwordx2 v[218:219], v235, s[14:15] offset:256
	global_load_dwordx2 v[220:221], v227, s[12:13] offset:288
	global_load_dwordx2 v[222:223], v235, s[14:15] offset:288
	s_waitcnt vmcnt(30)
	v_lshlrev_b32_e32 v132, 16, v160
	v_lshlrev_b32_e32 v134, 16, v162
	v_and_b32_e32 v133, 0xffff0000, v160
	v_and_b32_e32 v135, 0xffff0000, v162
	v_lshlrev_b32_e32 v136, 16, v161
	v_lshlrev_b32_e32 v138, 16, v163
	v_and_b32_e32 v137, 0xffff0000, v161
	v_and_b32_e32 v139, 0xffff0000, v163
	v_pk_fma_f32 v[124:125], v[124:125], v[132:133], v[134:135]
	v_pk_fma_f32 v[126:127], v[126:127], v[136:137], v[138:139]
	v_cvt_pk_bf16_f32 v140, v124, v125
	v_cvt_pk_bf16_f32 v141, v126, v127
	global_store_dwordx2 v232, v[140:141], s[14:15] offset:0
	global_load_dwordx2 v[160:161], v228, s[12:13] offset:0
	global_load_dwordx2 v[162:163], v236, s[14:15] offset:0
	s_waitcnt vmcnt(31)
	v_lshlrev_b32_e32 v132, 16, v164
	v_lshlrev_b32_e32 v134, 16, v166
	v_and_b32_e32 v133, 0xffff0000, v164
	v_and_b32_e32 v135, 0xffff0000, v166
	v_lshlrev_b32_e32 v136, 16, v165
	v_lshlrev_b32_e32 v138, 16, v167
	v_and_b32_e32 v137, 0xffff0000, v165
	v_and_b32_e32 v139, 0xffff0000, v167
	v_pk_fma_f32 v[120:121], v[120:121], v[132:133], v[134:135]
	v_pk_fma_f32 v[122:123], v[122:123], v[136:137], v[138:139]
	v_cvt_pk_bf16_f32 v142, v120, v121
	v_cvt_pk_bf16_f32 v143, v122, v123
	global_store_dwordx2 v232, v[142:143], s[14:15] offset:32
	global_load_dwordx2 v[164:165], v228, s[12:13] offset:32
	global_load_dwordx2 v[166:167], v236, s[14:15] offset:32
	s_waitcnt vmcnt(32)
	v_lshlrev_b32_e32 v132, 16, v168
	v_lshlrev_b32_e32 v134, 16, v170
	v_and_b32_e32 v133, 0xffff0000, v168
	v_and_b32_e32 v135, 0xffff0000, v170
	v_lshlrev_b32_e32 v136, 16, v169
	v_lshlrev_b32_e32 v138, 16, v171
	v_and_b32_e32 v137, 0xffff0000, v169
	v_and_b32_e32 v139, 0xffff0000, v171
	v_pk_fma_f32 v[116:117], v[116:117], v[132:133], v[134:135]
	v_pk_fma_f32 v[118:119], v[118:119], v[136:137], v[138:139]
	v_cvt_pk_bf16_f32 v140, v116, v117
	v_cvt_pk_bf16_f32 v141, v118, v119
	global_store_dwordx2 v233, v[140:141], s[14:15] offset:0
	global_load_dwordx2 v[168:169], v229, s[12:13] offset:0
	global_load_dwordx2 v[170:171], v237, s[14:15] offset:0
	s_waitcnt vmcnt(33)
	v_lshlrev_b32_e32 v132, 16, v172
	v_lshlrev_b32_e32 v134, 16, v174
	v_and_b32_e32 v133, 0xffff0000, v172
	v_and_b32_e32 v135, 0xffff0000, v174
	v_lshlrev_b32_e32 v136, 16, v173
	v_lshlrev_b32_e32 v138, 16, v175
	v_and_b32_e32 v137, 0xffff0000, v173
	v_and_b32_e32 v139, 0xffff0000, v175
	v_pk_fma_f32 v[112:113], v[112:113], v[132:133], v[134:135]
	v_pk_fma_f32 v[114:115], v[114:115], v[136:137], v[138:139]
	v_cvt_pk_bf16_f32 v142, v112, v113
	v_cvt_pk_bf16_f32 v143, v114, v115
	global_store_dwordx2 v233, v[142:143], s[14:15] offset:32
	global_load_dwordx2 v[172:173], v229, s[12:13] offset:32
	global_load_dwordx2 v[174:175], v237, s[14:15] offset:32
	s_waitcnt vmcnt(34)
; DI uint2 pk4(float a, float b, float c, float d) { uint2 o; o.x = pk2(a, b); o.y = pk2(c, d); return o; }
; DI void phaseF(int wv0, PP p, unsigned char* smem) {
;     ...
;     epi256(wv0, acc, brow, bcol, [&](int ai, int bj, int m, int n, int row, int col0, f32x4& v) {
;       const unsigned og = (unsigned)row * 2048u + (unsigned)col0, om = (unsigned)row * 1024u + (unsigned)col0;
;       const uint2 t = *(const uint2*)(MR + om);
;       const uint2 gq = *(const uint2*)(MG + og);
;       *(uint2*)(MR + om) =
;           pk4(__uint_as_float(gq.x << 16) * v[0] + __uint_as_float(t.x << 16), __uint_as_float(gq.x & 0xffff0000u) * v[1] + __uint_as_float(t.x & 0xffff0000u),
;               __uint_as_float(gq.y << 16) * v[2] + __uint_as_float(t.y << 16), __uint_as_float(gq.y & 0xffff0000u) * v[3] + __uint_as_float(t.y & 0xffff0000u));
;     });
	v_lshlrev_b32_e32 v132, 16, v176
	v_lshlrev_b32_e32 v134, 16, v178
	v_and_b32_e32 v133, 0xffff0000, v176
	v_and_b32_e32 v135, 0xffff0000, v178
	v_lshlrev_b32_e32 v136, 16, v177
	v_lshlrev_b32_e32 v138, 16, v179
	v_and_b32_e32 v137, 0xffff0000, v177
	v_and_b32_e32 v139, 0xffff0000, v179
	v_pk_fma_f32 v[108:109], v[108:109], v[132:133], v[134:135]
	v_pk_fma_f32 v[110:111], v[110:111], v[136:137], v[138:139]
	v_cvt_pk_bf16_f32 v140, v108, v109
	v_cvt_pk_bf16_f32 v141, v110, v111
	global_store_dwordx2 v234, v[140:141], s[14:15] offset:0
	global_load_dwordx2 v[176:177], v230, s[12:13] offset:0
	global_load_dwordx2 v[178:179], v238, s[14:15] offset:0
	s_waitcnt vmcnt(35)
	v_lshlrev_b32_e32 v132, 16, v180
	v_lshlrev_b32_e32 v134, 16, v182
	v_and_b32_e32 v133, 0xffff0000, v180
	v_and_b32_e32 v135, 0xffff0000, v182
	v_lshlrev_b32_e32 v136, 16, v181
	v_lshlrev_b32_e32 v138, 16, v183
	v_and_b32_e32 v137, 0xffff0000, v181
	v_and_b32_e32 v139, 0xffff0000, v183
	v_pk_fma_f32 v[104:105], v[104:105], v[132:133], v[134:135]
	v_pk_fma_f32 v[106:107], v[106:107], v[136:137], v[138:139]
	v_cvt_pk_bf16_f32 v142, v104, v105
	v_cvt_pk_bf16_f32 v143, v106, v107
	global_store_dwordx2 v234, v[142:143], s[14:15] offset:32
	global_load_dwordx2 v[180:181], v230, s[12:13] offset:32
	global_load_dwordx2 v[182:183], v238, s[14:15] offset:32
	s_waitcnt vmcnt(36)
	v_lshlrev_b32_e32 v132, 16, v184
	v_lshlrev_b32_e32 v134, 16, v186
	v_and_b32_e32 v133, 0xffff0000, v184
	v_and_b32_e32 v135, 0xffff0000, v186
	v_lshlrev_b32_e32 v136, 16, v185
	v_lshlrev_b32_e32 v138, 16, v187
	v_and_b32_e32 v137, 0xffff0000, v185
	v_and_b32_e32 v139, 0xffff0000, v187
	v_pk_fma_f32 v[100:101], v[100:101], v[132:133], v[134:135]
	v_pk_fma_f32 v[102:103], v[102:103], v[136:137], v[138:139]
	v_cvt_pk_bf16_f32 v140, v100, v101
	v_cvt_pk_bf16_f32 v141, v102, v103
	global_store_dwordx2 v235, v[140:141], s[14:15] offset:0
	global_load_dwordx2 v[184:185], v231, s[12:13] offset:0
	global_load_dwordx2 v[186:187], v239, s[14:15] offset:0
	s_waitcnt vmcnt(37)
	v_lshlrev_b32_e32 v132, 16, v188
	v_lshlrev_b32_e32 v134, 16, v190
	v_and_b32_e32 v133, 0xffff0000, v188
	v_and_b32_e32 v135, 0xffff0000, v190
	v_lshlrev_b32_e32 v136, 16, v189
	v_lshlrev_b32_e32 v138, 16, v191
	v_and_b32_e32 v137, 0xffff0000, v189
	v_and_b32_e32 v139, 0xffff0000, v191
	v_pk_fma_f32 v[96:97], v[96:97], v[132:133], v[134:135]
	v_pk_fma_f32 v[98:99], v[98:99], v[136:137], v[138:139]
	v_cvt_pk_bf16_f32 v142, v96, v97
	v_cvt_pk_bf16_f32 v143, v98, v99
	global_store_dwordx2 v235, v[142:143], s[14:15] offset:32
	global_load_dwordx2 v[188:189], v231, s[12:13] offset:32
	global_load_dwordx2 v[190:191], v239, s[14:15] offset:32
	s_waitcnt vmcnt(38)
	v_lshlrev_b32_e32 v132, 16, v192
	v_lshlrev_b32_e32 v134, 16, v194
	v_and_b32_e32 v133, 0xffff0000, v192
	v_and_b32_e32 v135, 0xffff0000, v194
	v_lshlrev_b32_e32 v136, 16, v193
	v_lshlrev_b32_e32 v138, 16, v195
	v_and_b32_e32 v137, 0xffff0000, v193
	v_and_b32_e32 v139, 0xffff0000, v195
	v_pk_fma_f32 v[92:93], v[92:93], v[132:133], v[134:135]
	v_pk_fma_f32 v[94:95], v[94:95], v[136:137], v[138:139]
	v_cvt_pk_bf16_f32 v140, v92, v93
	v_cvt_pk_bf16_f32 v141, v94, v95
	global_store_dwordx2 v232, v[140:141], s[14:15] offset:256
	global_load_dwordx2 v[192:193], v228, s[12:13] offset:256
	global_load_dwordx2 v[194:195], v236, s[14:15] offset:256
	s_waitcnt vmcnt(39)
	v_lshlrev_b32_e32 v132, 16, v196
	v_lshlrev_b32_e32 v134, 16, v198
	v_and_b32_e32 v133, 0xffff0000, v196
	v_and_b32_e32 v135, 0xffff0000, v198
	v_lshlrev_b32_e32 v136, 16, v197
	v_lshlrev_b32_e32 v138, 16, v199
	v_and_b32_e32 v137, 0xffff0000, v197
	v_and_b32_e32 v139, 0xffff0000, v199
	v_pk_fma_f32 v[88:89], v[88:89], v[132:133], v[134:135]
	v_pk_fma_f32 v[90:91], v[90:91], v[136:137], v[138:139]
	v_cvt_pk_bf16_f32 v142, v88, v89
	v_cvt_pk_bf16_f32 v143, v90, v91
	global_store_dwordx2 v232, v[142:143], s[14:15] offset:288
	global_load_dwordx2 v[196:197], v228, s[12:13] offset:288
	global_load_dwordx2 v[198:199], v236, s[14:15] offset:288
	s_waitcnt vmcnt(40)
	v_lshlrev_b32_e32 v132, 16, v200
	v_lshlrev_b32_e32 v134, 16, v202
	v_and_b32_e32 v133, 0xffff0000, v200
	v_and_b32_e32 v135, 0xffff0000, v202
	v_lshlrev_b32_e32 v136, 16, v201
	v_lshlrev_b32_e32 v138, 16, v203
	v_and_b32_e32 v137, 0xffff0000, v201
	v_and_b32_e32 v139, 0xffff0000, v203
	v_pk_fma_f32 v[84:85], v[84:85], v[132:133], v[134:135]
	v_pk_fma_f32 v[86:87], v[86:87], v[136:137], v[138:139]
	v_cvt_pk_bf16_f32 v140, v84, v85
	v_cvt_pk_bf16_f32 v141, v86, v87
	global_store_dwordx2 v233, v[140:141], s[14:15] offset:256
	global_load_dwordx2 v[200:201], v229, s[12:13] offset:256
	global_load_dwordx2 v[202:203], v237, s[14:15] offset:256
	s_waitcnt vmcnt(41)
	v_lshlrev_b32_e32 v132, 16, v204
	v_lshlrev_b32_e32 v134, 16, v206
	v_and_b32_e32 v133, 0xffff0000, v204
	v_and_b32_e32 v135, 0xffff0000, v206
	v_lshlrev_b32_e32 v136, 16, v205
	v_lshlrev_b32_e32 v138, 16, v207
	v_and_b32_e32 v137, 0xffff0000, v205
	v_and_b32_e32 v139, 0xffff0000, v207
	v_pk_fma_f32 v[80:81], v[80:81], v[132:133], v[134:135]
	v_pk_fma_f32 v[82:83], v[82:83], v[136:137], v[138:139]
	v_cvt_pk_bf16_f32 v142, v80, v81
	v_cvt_pk_bf16_f32 v143, v82, v83
	global_store_dwordx2 v233, v[142:143], s[14:15] offset:288
	global_load_dwordx2 v[204:205], v229, s[12:13] offset:288
	global_load_dwordx2 v[206:207], v237, s[14:15] offset:288
	s_waitcnt vmcnt(42)
; DI uint2 pk4(float a, float b, float c, float d) { uint2 o; o.x = pk2(a, b); o.y = pk2(c, d); return o; }
; DI void phaseF(int wv0, PP p, unsigned char* smem) {
;     ...
;     epi256(wv0, acc, brow, bcol, [&](int ai, int bj, int m, int n, int row, int col0, f32x4& v) {
;       const unsigned og = (unsigned)row * 2048u + (unsigned)col0, om = (unsigned)row * 1024u + (unsigned)col0;
;       const uint2 t = *(const uint2*)(MR + om);
;       const uint2 gq = *(const uint2*)(MG + og);
;       *(uint2*)(MR + om) =
;           pk4(__uint_as_float(gq.x << 16) * v[0] + __uint_as_float(t.x << 16), __uint_as_float(gq.x & 0xffff0000u) * v[1] + __uint_as_float(t.x & 0xffff0000u),
;               __uint_as_float(gq.y << 16) * v[2] + __uint_as_float(t.y << 16), __uint_as_float(gq.y & 0xffff0000u) * v[3] + __uint_as_float(t.y & 0xffff0000u));
;     });
	v_lshlrev_b32_e32 v132, 16, v208
	v_lshlrev_b32_e32 v134, 16, v210
	v_and_b32_e32 v133, 0xffff0000, v208
	v_and_b32_e32 v135, 0xffff0000, v210
	v_lshlrev_b32_e32 v136, 16, v209
	v_lshlrev_b32_e32 v138, 16, v211
	v_and_b32_e32 v137, 0xffff0000, v209
	v_and_b32_e32 v139, 0xffff0000, v211
	v_pk_fma_f32 v[76:77], v[76:77], v[132:133], v[134:135]
	v_pk_fma_f32 v[78:79], v[78:79], v[136:137], v[138:139]
	v_cvt_pk_bf16_f32 v140, v76, v77
	v_cvt_pk_bf16_f32 v141, v78, v79
	global_store_dwordx2 v234, v[140:141], s[14:15] offset:256
	global_load_dwordx2 v[208:209], v230, s[12:13] offset:256
	global_load_dwordx2 v[210:211], v238, s[14:15] offset:256
	s_waitcnt vmcnt(43)
	v_lshlrev_b32_e32 v132, 16, v212
	v_lshlrev_b32_e32 v134, 16, v214
	v_and_b32_e32 v133, 0xffff0000, v212
	v_and_b32_e32 v135, 0xffff0000, v214
	v_lshlrev_b32_e32 v136, 16, v213
	v_lshlrev_b32_e32 v138, 16, v215
	v_and_b32_e32 v137, 0xffff0000, v213
	v_and_b32_e32 v139, 0xffff0000, v215
	v_pk_fma_f32 v[72:73], v[72:73], v[132:133], v[134:135]
	v_pk_fma_f32 v[74:75], v[74:75], v[136:137], v[138:139]
	v_cvt_pk_bf16_f32 v142, v72, v73
	v_cvt_pk_bf16_f32 v143, v74, v75
	global_store_dwordx2 v234, v[142:143], s[14:15] offset:288
	global_load_dwordx2 v[212:213], v230, s[12:13] offset:288
	global_load_dwordx2 v[214:215], v238, s[14:15] offset:288
	s_waitcnt vmcnt(44)
	v_lshlrev_b32_e32 v132, 16, v216
	v_lshlrev_b32_e32 v134, 16, v218
	v_and_b32_e32 v133, 0xffff0000, v216
	v_and_b32_e32 v135, 0xffff0000, v218
	v_lshlrev_b32_e32 v136, 16, v217
	v_lshlrev_b32_e32 v138, 16, v219
	v_and_b32_e32 v137, 0xffff0000, v217
	v_and_b32_e32 v139, 0xffff0000, v219
	v_pk_fma_f32 v[68:69], v[68:69], v[132:133], v[134:135]
	v_pk_fma_f32 v[70:71], v[70:71], v[136:137], v[138:139]
	v_cvt_pk_bf16_f32 v140, v68, v69
	v_cvt_pk_bf16_f32 v141, v70, v71
	global_store_dwordx2 v235, v[140:141], s[14:15] offset:256
	global_load_dwordx2 v[216:217], v231, s[12:13] offset:256
	global_load_dwordx2 v[218:219], v239, s[14:15] offset:256
	s_waitcnt vmcnt(45)
	v_lshlrev_b32_e32 v132, 16, v220
	v_lshlrev_b32_e32 v134, 16, v222
	v_and_b32_e32 v133, 0xffff0000, v220
	v_and_b32_e32 v135, 0xffff0000, v222
	v_lshlrev_b32_e32 v136, 16, v221
	v_lshlrev_b32_e32 v138, 16, v223
	v_and_b32_e32 v137, 0xffff0000, v221
	v_and_b32_e32 v139, 0xffff0000, v223
	v_pk_fma_f32 v[64:65], v[64:65], v[132:133], v[134:135]
	v_pk_fma_f32 v[66:67], v[66:67], v[136:137], v[138:139]
	v_cvt_pk_bf16_f32 v142, v64, v65
	v_cvt_pk_bf16_f32 v143, v66, v67
	global_store_dwordx2 v235, v[142:143], s[14:15] offset:288
	global_load_dwordx2 v[220:221], v231, s[12:13] offset:288
	global_load_dwordx2 v[222:223], v239, s[14:15] offset:288
	s_waitcnt vmcnt(45)
	v_lshlrev_b32_e32 v132, 16, v160
	v_lshlrev_b32_e32 v134, 16, v162
	v_and_b32_e32 v133, 0xffff0000, v160
	v_and_b32_e32 v135, 0xffff0000, v162
	v_lshlrev_b32_e32 v136, 16, v161
	v_lshlrev_b32_e32 v138, 16, v163
	v_and_b32_e32 v137, 0xffff0000, v161
	v_and_b32_e32 v139, 0xffff0000, v163
	v_pk_fma_f32 v[60:61], v[60:61], v[132:133], v[134:135]
	v_pk_fma_f32 v[62:63], v[62:63], v[136:137], v[138:139]
	v_cvt_pk_bf16_f32 v140, v60, v61
	v_cvt_pk_bf16_f32 v141, v62, v63
	global_store_dwordx2 v236, v[140:141], s[14:15] offset:0
	s_waitcnt vmcnt(43)
	v_lshlrev_b32_e32 v132, 16, v164
	v_lshlrev_b32_e32 v134, 16, v166
	v_and_b32_e32 v133, 0xffff0000, v164
	v_and_b32_e32 v135, 0xffff0000, v166
	v_lshlrev_b32_e32 v136, 16, v165
	v_lshlrev_b32_e32 v138, 16, v167
	v_and_b32_e32 v137, 0xffff0000, v165
	v_and_b32_e32 v139, 0xffff0000, v167
	v_pk_fma_f32 v[56:57], v[56:57], v[132:133], v[134:135]
	v_pk_fma_f32 v[58:59], v[58:59], v[136:137], v[138:139]
	v_cvt_pk_bf16_f32 v142, v56, v57
	v_cvt_pk_bf16_f32 v143, v58, v59
	global_store_dwordx2 v236, v[142:143], s[14:15] offset:32
	s_waitcnt vmcnt(41)
	v_lshlrev_b32_e32 v132, 16, v168
	v_lshlrev_b32_e32 v134, 16, v170
	v_and_b32_e32 v133, 0xffff0000, v168
	v_and_b32_e32 v135, 0xffff0000, v170
	v_lshlrev_b32_e32 v136, 16, v169
	v_lshlrev_b32_e32 v138, 16, v171
	v_and_b32_e32 v137, 0xffff0000, v169
	v_and_b32_e32 v139, 0xffff0000, v171
	v_pk_fma_f32 v[52:53], v[52:53], v[132:133], v[134:135]
	v_pk_fma_f32 v[54:55], v[54:55], v[136:137], v[138:139]
	v_cvt_pk_bf16_f32 v140, v52, v53
	v_cvt_pk_bf16_f32 v141, v54, v55
	global_store_dwordx2 v237, v[140:141], s[14:15] offset:0
	s_waitcnt vmcnt(39)
	v_lshlrev_b32_e32 v132, 16, v172
	v_lshlrev_b32_e32 v134, 16, v174
	v_and_b32_e32 v133, 0xffff0000, v172
	v_and_b32_e32 v135, 0xffff0000, v174
	v_lshlrev_b32_e32 v136, 16, v173
	v_lshlrev_b32_e32 v138, 16, v175
	v_and_b32_e32 v137, 0xffff0000, v173
	v_and_b32_e32 v139, 0xffff0000, v175
	v_pk_fma_f32 v[48:49], v[48:49], v[132:133], v[134:135]
	v_pk_fma_f32 v[50:51], v[50:51], v[136:137], v[138:139]
	v_cvt_pk_bf16_f32 v142, v48, v49
	v_cvt_pk_bf16_f32 v143, v50, v51
	global_store_dwordx2 v237, v[142:143], s[14:15] offset:32
	s_waitcnt vmcnt(37)
	v_lshlrev_b32_e32 v132, 16, v176
	v_lshlrev_b32_e32 v134, 16, v178
	v_and_b32_e32 v133, 0xffff0000, v176
	v_and_b32_e32 v135, 0xffff0000, v178
	v_lshlrev_b32_e32 v136, 16, v177
	v_lshlrev_b32_e32 v138, 16, v179
	v_and_b32_e32 v137, 0xffff0000, v177
	v_and_b32_e32 v139, 0xffff0000, v179
	v_pk_fma_f32 v[44:45], v[44:45], v[132:133], v[134:135]
	v_pk_fma_f32 v[46:47], v[46:47], v[136:137], v[138:139]
	v_cvt_pk_bf16_f32 v140, v44, v45
	v_cvt_pk_bf16_f32 v141, v46, v47
	global_store_dwordx2 v238, v[140:141], s[14:15] offset:0
	s_waitcnt vmcnt(35)
; DI uint2 pk4(float a, float b, float c, float d) { uint2 o; o.x = pk2(a, b); o.y = pk2(c, d); return o; }
; DI void phaseF(int wv0, PP p, unsigned char* smem) {
;     ...
;   for (int id = blockIdx.x; id < 128 * 4; id += gridDim.x) {
;     ...
;     epi256(wv0, acc, brow, bcol, [&](int ai, int bj, int m, int n, int row, int col0, f32x4& v) {
;       const unsigned og = (unsigned)row * 2048u + (unsigned)col0, om = (unsigned)row * 1024u + (unsigned)col0;
;       const uint2 t = *(const uint2*)(MR + om);
;       const uint2 gq = *(const uint2*)(MG + og);
;       *(uint2*)(MR + om) =
;           pk4(__uint_as_float(gq.x << 16) * v[0] + __uint_as_float(t.x << 16), __uint_as_float(gq.x & 0xffff0000u) * v[1] + __uint_as_float(t.x & 0xffff0000u),
;               __uint_as_float(gq.y << 16) * v[2] + __uint_as_float(t.y << 16), __uint_as_float(gq.y & 0xffff0000u) * v[3] + __uint_as_float(t.y & 0xffff0000u));
;     });
	v_lshlrev_b32_e32 v132, 16, v180
	v_lshlrev_b32_e32 v134, 16, v182
	v_and_b32_e32 v133, 0xffff0000, v180
	v_and_b32_e32 v135, 0xffff0000, v182
	v_lshlrev_b32_e32 v136, 16, v181
	v_lshlrev_b32_e32 v138, 16, v183
	v_and_b32_e32 v137, 0xffff0000, v181
	v_and_b32_e32 v139, 0xffff0000, v183
	v_pk_fma_f32 v[40:41], v[40:41], v[132:133], v[134:135]
	v_pk_fma_f32 v[42:43], v[42:43], v[136:137], v[138:139]
	v_cvt_pk_bf16_f32 v142, v40, v41
	v_cvt_pk_bf16_f32 v143, v42, v43
	global_store_dwordx2 v238, v[142:143], s[14:15] offset:32
	s_waitcnt vmcnt(33)
	v_lshlrev_b32_e32 v132, 16, v184
	v_lshlrev_b32_e32 v134, 16, v186
	v_and_b32_e32 v133, 0xffff0000, v184
	v_and_b32_e32 v135, 0xffff0000, v186
	v_lshlrev_b32_e32 v136, 16, v185
	v_lshlrev_b32_e32 v138, 16, v187
	v_and_b32_e32 v137, 0xffff0000, v185
	v_and_b32_e32 v139, 0xffff0000, v187
	v_pk_fma_f32 v[36:37], v[36:37], v[132:133], v[134:135]
	v_pk_fma_f32 v[38:39], v[38:39], v[136:137], v[138:139]
	v_cvt_pk_bf16_f32 v140, v36, v37
	v_cvt_pk_bf16_f32 v141, v38, v39
	global_store_dwordx2 v239, v[140:141], s[14:15] offset:0
	s_waitcnt vmcnt(31)
	v_lshlrev_b32_e32 v132, 16, v188
	v_lshlrev_b32_e32 v134, 16, v190
	v_and_b32_e32 v133, 0xffff0000, v188
	v_and_b32_e32 v135, 0xffff0000, v190
	v_lshlrev_b32_e32 v136, 16, v189
	v_lshlrev_b32_e32 v138, 16, v191
	v_and_b32_e32 v137, 0xffff0000, v189
	v_and_b32_e32 v139, 0xffff0000, v191
	v_pk_fma_f32 v[32:33], v[32:33], v[132:133], v[134:135]
	v_pk_fma_f32 v[34:35], v[34:35], v[136:137], v[138:139]
	v_cvt_pk_bf16_f32 v142, v32, v33
	v_cvt_pk_bf16_f32 v143, v34, v35
	global_store_dwordx2 v239, v[142:143], s[14:15] offset:32
	s_waitcnt vmcnt(29)
	v_lshlrev_b32_e32 v132, 16, v192
	v_lshlrev_b32_e32 v134, 16, v194
	v_and_b32_e32 v133, 0xffff0000, v192
	v_and_b32_e32 v135, 0xffff0000, v194
	v_lshlrev_b32_e32 v136, 16, v193
	v_lshlrev_b32_e32 v138, 16, v195
	v_and_b32_e32 v137, 0xffff0000, v193
	v_and_b32_e32 v139, 0xffff0000, v195
	v_pk_fma_f32 v[28:29], v[28:29], v[132:133], v[134:135]
	v_pk_fma_f32 v[30:31], v[30:31], v[136:137], v[138:139]
	v_cvt_pk_bf16_f32 v140, v28, v29
	v_cvt_pk_bf16_f32 v141, v30, v31
	global_store_dwordx2 v236, v[140:141], s[14:15] offset:256
	s_waitcnt vmcnt(27)
	v_lshlrev_b32_e32 v132, 16, v196
	v_lshlrev_b32_e32 v134, 16, v198
	v_and_b32_e32 v133, 0xffff0000, v196
	v_and_b32_e32 v135, 0xffff0000, v198
	v_lshlrev_b32_e32 v136, 16, v197
	v_lshlrev_b32_e32 v138, 16, v199
	v_and_b32_e32 v137, 0xffff0000, v197
	v_and_b32_e32 v139, 0xffff0000, v199
	v_pk_fma_f32 v[24:25], v[24:25], v[132:133], v[134:135]
	v_pk_fma_f32 v[26:27], v[26:27], v[136:137], v[138:139]
	v_cvt_pk_bf16_f32 v142, v24, v25
	v_cvt_pk_bf16_f32 v143, v26, v27
	global_store_dwordx2 v236, v[142:143], s[14:15] offset:288
	s_waitcnt vmcnt(25)
	v_lshlrev_b32_e32 v132, 16, v200
	v_lshlrev_b32_e32 v134, 16, v202
	v_and_b32_e32 v133, 0xffff0000, v200
	v_and_b32_e32 v135, 0xffff0000, v202
	v_lshlrev_b32_e32 v136, 16, v201
	v_lshlrev_b32_e32 v138, 16, v203
	v_and_b32_e32 v137, 0xffff0000, v201
	v_and_b32_e32 v139, 0xffff0000, v203
	v_pk_fma_f32 v[20:21], v[20:21], v[132:133], v[134:135]
	v_pk_fma_f32 v[22:23], v[22:23], v[136:137], v[138:139]
	v_cvt_pk_bf16_f32 v140, v20, v21
	v_cvt_pk_bf16_f32 v141, v22, v23
	global_store_dwordx2 v237, v[140:141], s[14:15] offset:256
	s_waitcnt vmcnt(23)
	v_lshlrev_b32_e32 v132, 16, v204
	v_lshlrev_b32_e32 v134, 16, v206
	v_and_b32_e32 v133, 0xffff0000, v204
	v_and_b32_e32 v135, 0xffff0000, v206
	v_lshlrev_b32_e32 v136, 16, v205
	v_lshlrev_b32_e32 v138, 16, v207
	v_and_b32_e32 v137, 0xffff0000, v205
	v_and_b32_e32 v139, 0xffff0000, v207
	v_pk_fma_f32 v[16:17], v[16:17], v[132:133], v[134:135]
	v_pk_fma_f32 v[18:19], v[18:19], v[136:137], v[138:139]
	v_cvt_pk_bf16_f32 v142, v16, v17
	v_cvt_pk_bf16_f32 v143, v18, v19
	global_store_dwordx2 v237, v[142:143], s[14:15] offset:288
	s_waitcnt vmcnt(21)
	v_lshlrev_b32_e32 v132, 16, v208
	v_lshlrev_b32_e32 v134, 16, v210
	v_and_b32_e32 v133, 0xffff0000, v208
	v_and_b32_e32 v135, 0xffff0000, v210
	v_lshlrev_b32_e32 v136, 16, v209
	v_lshlrev_b32_e32 v138, 16, v211
	v_and_b32_e32 v137, 0xffff0000, v209
	v_and_b32_e32 v139, 0xffff0000, v211
	v_pk_fma_f32 v[12:13], v[12:13], v[132:133], v[134:135]
	v_pk_fma_f32 v[14:15], v[14:15], v[136:137], v[138:139]
	v_cvt_pk_bf16_f32 v140, v12, v13
	v_cvt_pk_bf16_f32 v141, v14, v15
	global_store_dwordx2 v238, v[140:141], s[14:15] offset:256
	s_waitcnt vmcnt(19)
	v_lshlrev_b32_e32 v132, 16, v212
	v_lshlrev_b32_e32 v134, 16, v214
	v_and_b32_e32 v133, 0xffff0000, v212
	v_and_b32_e32 v135, 0xffff0000, v214
	v_lshlrev_b32_e32 v136, 16, v213
	v_lshlrev_b32_e32 v138, 16, v215
	v_and_b32_e32 v137, 0xffff0000, v213
	v_and_b32_e32 v139, 0xffff0000, v215
	v_pk_fma_f32 v[8:9], v[8:9], v[132:133], v[134:135]
	v_pk_fma_f32 v[10:11], v[10:11], v[136:137], v[138:139]
	v_cvt_pk_bf16_f32 v142, v8, v9
	v_cvt_pk_bf16_f32 v143, v10, v11
	global_store_dwordx2 v238, v[142:143], s[14:15] offset:288
	s_waitcnt vmcnt(17)
	v_lshlrev_b32_e32 v132, 16, v216
	v_lshlrev_b32_e32 v134, 16, v218
	v_and_b32_e32 v133, 0xffff0000, v216
	v_and_b32_e32 v135, 0xffff0000, v218
	v_lshlrev_b32_e32 v136, 16, v217
	v_lshlrev_b32_e32 v138, 16, v219
	v_and_b32_e32 v137, 0xffff0000, v217
	v_and_b32_e32 v139, 0xffff0000, v219
	v_pk_fma_f32 v[4:5], v[4:5], v[132:133], v[134:135]
	v_pk_fma_f32 v[6:7], v[6:7], v[136:137], v[138:139]
	v_cvt_pk_bf16_f32 v140, v4, v5
	v_cvt_pk_bf16_f32 v141, v6, v7
	global_store_dwordx2 v239, v[140:141], s[14:15] offset:256
	s_waitcnt vmcnt(15)
	v_lshlrev_b32_e32 v132, 16, v220
	v_lshlrev_b32_e32 v134, 16, v222
	v_and_b32_e32 v133, 0xffff0000, v220
	v_and_b32_e32 v135, 0xffff0000, v222
	v_lshlrev_b32_e32 v136, 16, v221
	v_lshlrev_b32_e32 v138, 16, v223
	v_and_b32_e32 v137, 0xffff0000, v221
	v_and_b32_e32 v139, 0xffff0000, v223
	v_pk_fma_f32 v[0:1], v[0:1], v[132:133], v[134:135]
	v_pk_fma_f32 v[2:3], v[2:3], v[136:137], v[138:139]
	v_cvt_pk_bf16_f32 v142, v0, v1
	v_cvt_pk_bf16_f32 v143, v2, v3
	global_store_dwordx2 v239, v[142:143], s[14:15] offset:288
	s_load_dword s0, s[20:21], 0x0
	s_waitcnt lgkmcnt(0)
	s_add_i32 s93, s0, s93
	s_cmpk_gt_i32 s93, 0x1ff
	s_cbranch_scc1 .LBB0_995

; DI uint2 pk4(float a, float b, float c, float d) { uint2 o; o.x = pk2(a, b); o.y = pk2(c, d); return o; }
; DI void phaseG(int wv0, PP p, unsigned char* smem) {
;     ...
;     epi256(wv0, acc, brow, bcol, [&](int ai, int bj, int m, int n, int row, int col0, f32x4& v) {
;       const size_t o = (size_t)row * 1024 + col0;
;       const float4 xv = *(const float4*)(p->x + o);
;       v[0] += xv.x; v[1] += xv.y; v[2] += xv.z; v[3] += xv.w;
;       *(uint2*)(X1B + o) = pk4(v[0], v[1], v[2], v[3]);
;     });
.LBB0_1060:
	s_load_dwordx2 s[48:49], s[4:5], 0x0
	s_add_i32 s47, s46, s55
	s_lshl_b32 s8, s68, 8
	s_or_b32 s8, s8, s56
	v_and_or_b32 v128, v140, 15, s47
	v_lshrrev_b32_e32 v129, 2, v140
	v_and_or_b32 v130, v129, 12, s8
	v_lshlrev_b32_e32 v131, 12, v128
	v_lshl_add_u32 v224, v130, 2, v131
	v_lshlrev_b32_e32 v131, 11, v128
	v_lshl_add_u32 v232, v130, 1, v131
	v_add_u32_e32 v225, 0x10000, v224
	v_add_u32_e32 v233, 0x8000, v232
	v_add_u32_e32 v226, 0x20000, v224
	v_add_u32_e32 v234, 0x10000, v232
	v_add_u32_e32 v227, 0x30000, v224
	v_add_u32_e32 v235, 0x18000, v232
	v_add_u32_e32 v228, 0x80000, v224
	v_add_u32_e32 v236, 0x40000, v232
	v_add_u32_e32 v229, 0x90000, v224
	v_add_u32_e32 v237, 0x48000, v232
	v_add_u32_e32 v230, 0xa0000, v224
	v_add_u32_e32 v238, 0x50000, v232
	v_add_u32_e32 v231, 0xb0000, v224
	v_add_u32_e32 v239, 0x58000, v232
	s_waitcnt lgkmcnt(0)
	global_load_dwordx4 v[144:147], v224, s[48:49] offset:0
	global_load_dwordx4 v[148:151], v224, s[48:49] offset:64
	global_load_dwordx4 v[152:155], v225, s[48:49] offset:0
	global_load_dwordx4 v[156:159], v225, s[48:49] offset:64
	global_load_dwordx4 v[160:163], v226, s[48:49] offset:0
	global_load_dwordx4 v[164:167], v226, s[48:49] offset:64
	global_load_dwordx4 v[168:171], v227, s[48:49] offset:0
	global_load_dwordx4 v[172:175], v227, s[48:49] offset:64
	global_load_dwordx4 v[176:179], v224, s[48:49] offset:512
	global_load_dwordx4 v[180:183], v224, s[48:49] offset:576
	global_load_dwordx4 v[184:187], v225, s[48:49] offset:512
	global_load_dwordx4 v[188:191], v225, s[48:49] offset:576
	global_load_dwordx4 v[192:195], v226, s[48:49] offset:512
	global_load_dwordx4 v[196:199], v226, s[48:49] offset:576
	global_load_dwordx4 v[200:203], v227, s[48:49] offset:512
	global_load_dwordx4 v[204:207], v227, s[48:49] offset:576
	global_load_dwordx4 v[208:211], v228, s[48:49] offset:0
	global_load_dwordx4 v[212:215], v228, s[48:49] offset:64
	global_load_dwordx4 v[216:219], v229, s[48:49] offset:0
	global_load_dwordx4 v[220:223], v229, s[48:49] offset:64
	s_waitcnt vmcnt(19)
	v_pk_add_f32 v[124:125], v[124:125], v[144:145]
	v_pk_add_f32 v[126:127], v[126:127], v[146:147]
	v_cvt_pk_bf16_f32 v132, v124, v125
	v_cvt_pk_bf16_f32 v133, v126, v127
	global_store_dwordx2 v232, v[132:133], s[10:11] offset:0
	global_load_dwordx4 v[144:147], v230, s[48:49] offset:0
	s_waitcnt vmcnt(20)
	v_pk_add_f32 v[120:121], v[120:121], v[148:149]
	v_pk_add_f32 v[122:123], v[122:123], v[150:151]
	v_cvt_pk_bf16_f32 v134, v120, v121
	v_cvt_pk_bf16_f32 v135, v122, v123
	global_store_dwordx2 v232, v[134:135], s[10:11] offset:32
	global_load_dwordx4 v[148:151], v230, s[48:49] offset:64
	s_waitcnt vmcnt(21)
	v_pk_add_f32 v[116:117], v[116:117], v[152:153]
	v_pk_add_f32 v[118:119], v[118:119], v[154:155]
	v_cvt_pk_bf16_f32 v132, v116, v117
	v_cvt_pk_bf16_f32 v133, v118, v119
	global_store_dwordx2 v233, v[132:133], s[10:11] offset:0
	global_load_dwordx4 v[152:155], v231, s[48:49] offset:0
	s_waitcnt vmcnt(22)
	v_pk_add_f32 v[112:113], v[112:113], v[156:157]
	v_pk_add_f32 v[114:115], v[114:115], v[158:159]
	v_cvt_pk_bf16_f32 v134, v112, v113
	v_cvt_pk_bf16_f32 v135, v114, v115
	global_store_dwordx2 v233, v[134:135], s[10:11] offset:32
	global_load_dwordx4 v[156:159], v231, s[48:49] offset:64
	s_waitcnt vmcnt(23)
	v_pk_add_f32 v[108:109], v[108:109], v[160:161]
	v_pk_add_f32 v[110:111], v[110:111], v[162:163]
	v_cvt_pk_bf16_f32 v132, v108, v109
	v_cvt_pk_bf16_f32 v133, v110, v111
	global_store_dwordx2 v234, v[132:133], s[10:11] offset:0
	global_load_dwordx4 v[160:163], v228, s[48:49] offset:512
	s_waitcnt vmcnt(24)
	v_pk_add_f32 v[104:105], v[104:105], v[164:165]
	v_pk_add_f32 v[106:107], v[106:107], v[166:167]
	v_cvt_pk_bf16_f32 v134, v104, v105
	v_cvt_pk_bf16_f32 v135, v106, v107
	global_store_dwordx2 v234, v[134:135], s[10:11] offset:32
	global_load_dwordx4 v[164:167], v228, s[48:49] offset:576
	s_waitcnt vmcnt(25)
	v_pk_add_f32 v[100:101], v[100:101], v[168:169]
	v_pk_add_f32 v[102:103], v[102:103], v[170:171]
	v_cvt_pk_bf16_f32 v132, v100, v101
	v_cvt_pk_bf16_f32 v133, v102, v103
	global_store_dwordx2 v235, v[132:133], s[10:11] offset:0
	global_load_dwordx4 v[168:171], v229, s[48:49] offset:512
	s_waitcnt vmcnt(26)
	v_pk_add_f32 v[96:97], v[96:97], v[172:173]
	v_pk_add_f32 v[98:99], v[98:99], v[174:175]
	v_cvt_pk_bf16_f32 v134, v96, v97
	v_cvt_pk_bf16_f32 v135, v98, v99
	global_store_dwordx2 v235, v[134:135], s[10:11] offset:32
	global_load_dwordx4 v[172:175], v229, s[48:49] offset:576
	s_waitcnt vmcnt(27)
	v_pk_add_f32 v[92:93], v[92:93], v[176:177]
	v_pk_add_f32 v[94:95], v[94:95], v[178:179]
	v_cvt_pk_bf16_f32 v132, v92, v93
	v_cvt_pk_bf16_f32 v133, v94, v95
	global_store_dwordx2 v232, v[132:133], s[10:11] offset:256
	global_load_dwordx4 v[176:179], v230, s[48:49] offset:512
	s_waitcnt vmcnt(28)
	v_pk_add_f32 v[88:89], v[88:89], v[180:181]
	v_pk_add_f32 v[90:91], v[90:91], v[182:183]
	v_cvt_pk_bf16_f32 v134, v88, v89
	v_cvt_pk_bf16_f32 v135, v90, v91
	global_store_dwordx2 v232, v[134:135], s[10:11] offset:288
	global_load_dwordx4 v[180:183], v230, s[48:49] offset:576
	s_waitcnt vmcnt(29)
	v_pk_add_f32 v[84:85], v[84:85], v[184:185]
	v_pk_add_f32 v[86:87], v[86:87], v[186:187]
	v_cvt_pk_bf16_f32 v132, v84, v85
	v_cvt_pk_bf16_f32 v133, v86, v87
	global_store_dwordx2 v233, v[132:133], s[10:11] offset:256
	global_load_dwordx4 v[184:187], v231, s[48:49] offset:512
	s_waitcnt vmcnt(30)
	v_pk_add_f32 v[80:81], v[80:81], v[188:189]
	v_pk_add_f32 v[82:83], v[82:83], v[190:191]
	v_cvt_pk_bf16_f32 v134, v80, v81
	v_cvt_pk_bf16_f32 v135, v82, v83
	global_store_dwordx2 v233, v[134:135], s[10:11] offset:288
	global_load_dwordx4 v[188:191], v231, s[48:49] offset:576
	s_waitcnt vmcnt(31)
; DI uint2 pk4(float a, float b, float c, float d) { uint2 o; o.x = pk2(a, b); o.y = pk2(c, d); return o; }
; DI void ss_partial(int wv0, f32x4 (&acc)[2][2][4][2], float* SS, int brow, int pn) {
;   const int lane = my_tid(wv0) & 63, wr = wv0 >> 2, wc = wv0 & 3;
; #pragma unroll
;   for (int ai = 0; ai < 2; ++ai)
; #pragma unroll
;     for (int m = 0; m < 4; ++m) {
;       float s = 0.f;
; #pragma unroll
;       for (int bj = 0; bj < 2; ++bj)
; #pragma unroll
;         for (int n = 0; n < 2; ++n)
; #pragma unroll
;           for (int j = 0; j < 4; ++j) s += acc[ai][bj][m][n][j] * acc[ai][bj][m][n][j];
;       s += __shfl_xor(s, 16);
;       s += __shfl_xor(s, 32);
;       if (lane < 16) SS[(size_t)(brow + ai * 128 + wr * 64 + m * 16 + lane) * 16 + pn * 4 + wc] = s;
;     }
; DI void phaseG(int wv0, PP p, unsigned char* smem) {
;     ...
;     epi256(wv0, acc, brow, bcol, [&](int ai, int bj, int m, int n, int row, int col0, f32x4& v) {
;       const size_t o = (size_t)row * 1024 + col0;
;       const float4 xv = *(const float4*)(p->x + o);
;       v[0] += xv.x; v[1] += xv.y; v[2] += xv.z; v[3] += xv.w;
;       *(uint2*)(X1B + o) = pk4(v[0], v[1], v[2], v[3]);
;     });
;     ss_partial(wv0, acc, SS1, brow, pn);
	v_pk_add_f32 v[76:77], v[76:77], v[192:193]
	v_pk_add_f32 v[78:79], v[78:79], v[194:195]
	v_cvt_pk_bf16_f32 v132, v76, v77
	v_cvt_pk_bf16_f32 v133, v78, v79
	global_store_dwordx2 v234, v[132:133], s[10:11] offset:256
	s_waitcnt vmcnt(31)
	v_pk_add_f32 v[72:73], v[72:73], v[196:197]
	v_pk_add_f32 v[74:75], v[74:75], v[198:199]
	v_cvt_pk_bf16_f32 v134, v72, v73
	v_cvt_pk_bf16_f32 v135, v74, v75
	global_store_dwordx2 v234, v[134:135], s[10:11] offset:288
	s_waitcnt vmcnt(31)
	v_pk_add_f32 v[68:69], v[68:69], v[200:201]
	v_pk_add_f32 v[70:71], v[70:71], v[202:203]
	v_cvt_pk_bf16_f32 v132, v68, v69
	v_cvt_pk_bf16_f32 v133, v70, v71
	global_store_dwordx2 v235, v[132:133], s[10:11] offset:256
	s_waitcnt vmcnt(31)
	v_pk_add_f32 v[64:65], v[64:65], v[204:205]
	v_pk_add_f32 v[66:67], v[66:67], v[206:207]
	v_cvt_pk_bf16_f32 v134, v64, v65
	v_cvt_pk_bf16_f32 v135, v66, v67
	global_store_dwordx2 v235, v[134:135], s[10:11] offset:288
	s_waitcnt vmcnt(31)
	v_pk_add_f32 v[60:61], v[60:61], v[208:209]
	v_pk_add_f32 v[62:63], v[62:63], v[210:211]
	v_cvt_pk_bf16_f32 v132, v60, v61
	v_cvt_pk_bf16_f32 v133, v62, v63
	global_store_dwordx2 v236, v[132:133], s[10:11] offset:0
	s_waitcnt vmcnt(31)
	v_pk_add_f32 v[56:57], v[56:57], v[212:213]
	v_pk_add_f32 v[58:59], v[58:59], v[214:215]
	v_cvt_pk_bf16_f32 v134, v56, v57
	v_cvt_pk_bf16_f32 v135, v58, v59
	global_store_dwordx2 v236, v[134:135], s[10:11] offset:32
	s_waitcnt vmcnt(31)
	v_pk_add_f32 v[52:53], v[52:53], v[216:217]
	v_pk_add_f32 v[54:55], v[54:55], v[218:219]
	v_cvt_pk_bf16_f32 v132, v52, v53
	v_cvt_pk_bf16_f32 v133, v54, v55
	global_store_dwordx2 v237, v[132:133], s[10:11] offset:0
	s_waitcnt vmcnt(31)
	v_pk_add_f32 v[48:49], v[48:49], v[220:221]
	v_pk_add_f32 v[50:51], v[50:51], v[222:223]
	v_cvt_pk_bf16_f32 v134, v48, v49
	v_cvt_pk_bf16_f32 v135, v50, v51
	global_store_dwordx2 v237, v[134:135], s[10:11] offset:32
	s_waitcnt vmcnt(30)
	v_pk_add_f32 v[44:45], v[44:45], v[144:145]
	v_pk_add_f32 v[46:47], v[46:47], v[146:147]
	v_cvt_pk_bf16_f32 v132, v44, v45
	v_cvt_pk_bf16_f32 v133, v46, v47
	global_store_dwordx2 v238, v[132:133], s[10:11] offset:0
	s_waitcnt vmcnt(29)
	v_pk_add_f32 v[40:41], v[40:41], v[148:149]
	v_pk_add_f32 v[42:43], v[42:43], v[150:151]
	v_cvt_pk_bf16_f32 v134, v40, v41
	v_cvt_pk_bf16_f32 v135, v42, v43
	global_store_dwordx2 v238, v[134:135], s[10:11] offset:32
	s_waitcnt vmcnt(28)
	v_pk_add_f32 v[36:37], v[36:37], v[152:153]
	v_pk_add_f32 v[38:39], v[38:39], v[154:155]
	v_cvt_pk_bf16_f32 v132, v36, v37
	v_cvt_pk_bf16_f32 v133, v38, v39
	global_store_dwordx2 v239, v[132:133], s[10:11] offset:0
	s_waitcnt vmcnt(27)
	v_pk_add_f32 v[32:33], v[32:33], v[156:157]
	v_pk_add_f32 v[34:35], v[34:35], v[158:159]
	v_cvt_pk_bf16_f32 v134, v32, v33
	v_cvt_pk_bf16_f32 v135, v34, v35
	global_store_dwordx2 v239, v[134:135], s[10:11] offset:32
	s_waitcnt vmcnt(26)
	v_pk_add_f32 v[28:29], v[28:29], v[160:161]
	v_pk_add_f32 v[30:31], v[30:31], v[162:163]
	v_cvt_pk_bf16_f32 v132, v28, v29
	v_cvt_pk_bf16_f32 v133, v30, v31
	global_store_dwordx2 v236, v[132:133], s[10:11] offset:256
	s_waitcnt vmcnt(25)
	v_pk_add_f32 v[24:25], v[24:25], v[164:165]
	v_pk_add_f32 v[26:27], v[26:27], v[166:167]
	v_cvt_pk_bf16_f32 v134, v24, v25
	v_cvt_pk_bf16_f32 v135, v26, v27
	global_store_dwordx2 v236, v[134:135], s[10:11] offset:288
	s_waitcnt vmcnt(24)
	v_pk_add_f32 v[20:21], v[20:21], v[168:169]
	v_pk_add_f32 v[22:23], v[22:23], v[170:171]
	v_cvt_pk_bf16_f32 v132, v20, v21
	v_cvt_pk_bf16_f32 v133, v22, v23
	global_store_dwordx2 v237, v[132:133], s[10:11] offset:256
	s_waitcnt vmcnt(23)
	v_pk_add_f32 v[16:17], v[16:17], v[172:173]
	v_pk_add_f32 v[18:19], v[18:19], v[174:175]
	v_cvt_pk_bf16_f32 v134, v16, v17
	v_cvt_pk_bf16_f32 v135, v18, v19
	global_store_dwordx2 v237, v[134:135], s[10:11] offset:288
	s_waitcnt vmcnt(22)
	v_pk_add_f32 v[12:13], v[12:13], v[176:177]
	v_pk_add_f32 v[14:15], v[14:15], v[178:179]
	v_cvt_pk_bf16_f32 v132, v12, v13
	v_cvt_pk_bf16_f32 v133, v14, v15
	global_store_dwordx2 v238, v[132:133], s[10:11] offset:256
	s_waitcnt vmcnt(21)
	v_pk_add_f32 v[8:9], v[8:9], v[180:181]
	v_pk_add_f32 v[10:11], v[10:11], v[182:183]
	v_cvt_pk_bf16_f32 v134, v8, v9
	v_cvt_pk_bf16_f32 v135, v10, v11
	global_store_dwordx2 v238, v[134:135], s[10:11] offset:288
	s_waitcnt vmcnt(20)
	v_pk_add_f32 v[4:5], v[4:5], v[184:185]
	v_pk_add_f32 v[6:7], v[6:7], v[186:187]
	v_cvt_pk_bf16_f32 v132, v4, v5
	v_cvt_pk_bf16_f32 v133, v6, v7
	global_store_dwordx2 v239, v[132:133], s[10:11] offset:256
	s_waitcnt vmcnt(19)
	v_pk_add_f32 v[0:1], v[0:1], v[188:189]
	v_pk_add_f32 v[2:3], v[2:3], v[190:191]
	v_cvt_pk_bf16_f32 v134, v0, v1
	v_cvt_pk_bf16_f32 v135, v2, v3
	global_store_dwordx2 v239, v[134:135], s[10:11] offset:288
	v_pk_mul_f32 v[124:125], v[124:125], v[124:125]
	v_pk_mul_f32 v[126:127], v[126:127], v[126:127]
	v_add_f32_e32 v124, v124, v125
	v_add_f32_e32 v124, v124, v126
	v_pk_mul_f32 v[120:121], v[120:121], v[120:121]
	v_add_f32_e32 v124, v124, v127
	v_add_f32_e32 v120, v124, v120
	v_pk_mul_f32 v[122:123], v[122:123], v[122:123]
	v_add_f32_e32 v120, v120, v121
	v_add_f32_e32 v120, v120, v122
	v_pk_mul_f32 v[92:93], v[92:93], v[92:93]
	v_add_f32_e32 v120, v120, v123
	v_add_f32_e32 v92, v120, v92
	v_pk_mul_f32 v[94:95], v[94:95], v[94:95]
	v_add_f32_e32 v92, v92, v93
	v_add_f32_e32 v92, v92, v94
	v_pk_mul_f32 v[88:89], v[88:89], v[88:89]
	v_add_f32_e32 v92, v92, v95
	v_add_f32_e32 v88, v92, v88
	v_pk_mul_f32 v[90:91], v[90:91], v[90:91]
	v_add_f32_e32 v88, v88, v89
	v_add_f32_e32 v88, v88, v90
	v_add_f32_e32 v88, v88, v91
	ds_bpermute_b32 v89, v141, v88
	v_mov_b32_e32 v128, v140
	s_lshl_b32 s8, s68, 4
	v_and_b32_e32 v90, 63, v128
	s_waitcnt lgkmcnt(0)
	v_add_f32_e32 v89, v88, v89
	v_cmp_gt_u32_e32 vcc, 16, v90
	v_or_b32_e32 v91, s46, v90
	ds_bpermute_b32 v90, v142, v89
	s_add_u32 s46, s57, s8
	v_add_u32_e32 v88, s55, v91
	s_addc_u32 s47, s58, 0
	s_and_saveexec_b64 s[48:49], vcc
	s_cbranch_execz .LBB0_1062
	s_waitcnt lgkmcnt(0)
	v_add_f32_e32 v92, v89, v90
	v_ashrrev_i32_e32 v89, 31, v88
	v_lshlrev_b64 v[90:91], 6, v[88:89]
	v_lshl_add_u64 v[90:91], s[46:47], 0, v[90:91]
	global_store_dword v[90:91], v92, off

; DI void phaseI(int wv0, PP p, unsigned char* smem) {
;     ...
;     epi256(wv0, acc, brow, bcol, [&](int ai, int bj, int m, int n, int row, int col0, f32x4& v) {
;       const size_t o = (size_t)row * 1024 + col0;
;       const uint2 xb = *(const uint2*)(X1B + o);
;       v[0] += __uint_as_float(xb.x << 16); v[1] += __uint_as_float(xb.x & 0xffff0000u);
;       v[2] += __uint_as_float(xb.y << 16); v[3] += __uint_as_float(xb.y & 0xffff0000u);
;       *(float4*)(p->out + o) = make_float4(v[0], v[1], v[2], v[3]);
;     });
.LBB0_1206:
	s_load_dwordx2 s[48:49], s[4:5], 0xc0
	s_add_i32 s47, s46, s55
	s_lshl_b32 s8, s68, 8
	s_or_b32 s8, s8, s56
	v_and_or_b32 v128, v144, 15, s47
	v_lshrrev_b32_e32 v129, 2, v144
	v_and_or_b32 v130, v129, 12, s8
	v_lshlrev_b32_e32 v131, 11, v128
	v_lshl_add_u32 v224, v130, 1, v131
	v_lshlrev_b32_e32 v131, 12, v128
	v_lshl_add_u32 v232, v130, 2, v131
	v_add_u32_e32 v225, 0x8000, v224
	v_add_u32_e32 v233, 0x10000, v232
	v_add_u32_e32 v226, 0x10000, v224
	v_add_u32_e32 v234, 0x20000, v232
	v_add_u32_e32 v227, 0x18000, v224
	v_add_u32_e32 v235, 0x30000, v232
	v_add_u32_e32 v228, 0x40000, v224
	v_add_u32_e32 v236, 0x80000, v232
	v_add_u32_e32 v229, 0x48000, v224
	v_add_u32_e32 v237, 0x90000, v232
	v_add_u32_e32 v230, 0x50000, v224
	v_add_u32_e32 v238, 0xa0000, v232
	v_add_u32_e32 v231, 0x58000, v224
	v_add_u32_e32 v239, 0xb0000, v232
	global_load_dwordx2 v[148:149], v224, s[10:11] offset:0
	global_load_dwordx2 v[150:151], v224, s[10:11] offset:32
	global_load_dwordx2 v[152:153], v225, s[10:11] offset:0
	global_load_dwordx2 v[154:155], v225, s[10:11] offset:32
	global_load_dwordx2 v[156:157], v226, s[10:11] offset:0
	global_load_dwordx2 v[158:159], v226, s[10:11] offset:32
	global_load_dwordx2 v[160:161], v227, s[10:11] offset:0
	global_load_dwordx2 v[162:163], v227, s[10:11] offset:32
	global_load_dwordx2 v[164:165], v224, s[10:11] offset:256
	global_load_dwordx2 v[166:167], v224, s[10:11] offset:288
	global_load_dwordx2 v[168:169], v225, s[10:11] offset:256
	global_load_dwordx2 v[170:171], v225, s[10:11] offset:288
	global_load_dwordx2 v[172:173], v226, s[10:11] offset:256
	global_load_dwordx2 v[174:175], v226, s[10:11] offset:288
	global_load_dwordx2 v[176:177], v227, s[10:11] offset:256
	global_load_dwordx2 v[178:179], v227, s[10:11] offset:288
	global_load_dwordx2 v[180:181], v228, s[10:11] offset:0
	global_load_dwordx2 v[182:183], v228, s[10:11] offset:32
	global_load_dwordx2 v[184:185], v229, s[10:11] offset:0
	global_load_dwordx2 v[186:187], v229, s[10:11] offset:32
	s_waitcnt lgkmcnt(0)
	s_waitcnt vmcnt(19)
	v_lshlrev_b32_e32 v132, 16, v148
	v_and_b32_e32 v133, 0xffff0000, v148
	v_lshlrev_b32_e32 v134, 16, v149
	v_and_b32_e32 v135, 0xffff0000, v149
	v_pk_add_f32 v[12:13], v[12:13], v[132:133]
	v_pk_add_f32 v[14:15], v[14:15], v[134:135]
	global_store_dwordx4 v232, v[12:15], s[48:49] offset:0
	global_load_dwordx2 v[148:149], v230, s[10:11] offset:0
	s_waitcnt vmcnt(20)
	v_lshlrev_b32_e32 v136, 16, v150
	v_and_b32_e32 v137, 0xffff0000, v150
	v_lshlrev_b32_e32 v138, 16, v151
	v_and_b32_e32 v139, 0xffff0000, v151
	v_pk_add_f32 v[28:29], v[28:29], v[136:137]
	v_pk_add_f32 v[30:31], v[30:31], v[138:139]
	global_store_dwordx4 v232, v[28:31], s[48:49] offset:64
	global_load_dwordx2 v[150:151], v230, s[10:11] offset:32
	s_waitcnt vmcnt(21)
	v_lshlrev_b32_e32 v132, 16, v152
	v_and_b32_e32 v133, 0xffff0000, v152
	v_lshlrev_b32_e32 v134, 16, v153
	v_and_b32_e32 v135, 0xffff0000, v153
	v_pk_add_f32 v[16:17], v[16:17], v[132:133]
	v_pk_add_f32 v[18:19], v[18:19], v[134:135]
	global_store_dwordx4 v233, v[16:19], s[48:49] offset:0
	global_load_dwordx2 v[152:153], v231, s[10:11] offset:0
	s_waitcnt vmcnt(22)
	v_lshlrev_b32_e32 v136, 16, v154
	v_and_b32_e32 v137, 0xffff0000, v154
	v_lshlrev_b32_e32 v138, 16, v155
	v_and_b32_e32 v139, 0xffff0000, v155
	v_pk_add_f32 v[20:21], v[20:21], v[136:137]
	v_pk_add_f32 v[22:23], v[22:23], v[138:139]
	global_store_dwordx4 v233, v[20:23], s[48:49] offset:64
	global_load_dwordx2 v[154:155], v231, s[10:11] offset:32
	s_waitcnt vmcnt(23)
	v_lshlrev_b32_e32 v132, 16, v156
	v_and_b32_e32 v133, 0xffff0000, v156
	v_lshlrev_b32_e32 v134, 16, v157
	v_and_b32_e32 v135, 0xffff0000, v157
	v_pk_add_f32 v[32:33], v[32:33], v[132:133]
	v_pk_add_f32 v[34:35], v[34:35], v[134:135]
	global_store_dwordx4 v234, v[32:35], s[48:49] offset:0
	global_load_dwordx2 v[156:157], v228, s[10:11] offset:256
	s_waitcnt vmcnt(24)
	v_lshlrev_b32_e32 v136, 16, v158
	v_and_b32_e32 v137, 0xffff0000, v158
	v_lshlrev_b32_e32 v138, 16, v159
	v_and_b32_e32 v139, 0xffff0000, v159
	v_pk_add_f32 v[48:49], v[48:49], v[136:137]
	v_pk_add_f32 v[50:51], v[50:51], v[138:139]
	global_store_dwordx4 v234, v[48:51], s[48:49] offset:64
	global_load_dwordx2 v[158:159], v228, s[10:11] offset:288
	s_waitcnt vmcnt(25)
	v_lshlrev_b32_e32 v132, 16, v160
	v_and_b32_e32 v133, 0xffff0000, v160
	v_lshlrev_b32_e32 v134, 16, v161
	v_and_b32_e32 v135, 0xffff0000, v161
	v_pk_add_f32 v[36:37], v[36:37], v[132:133]
	v_pk_add_f32 v[38:39], v[38:39], v[134:135]
	global_store_dwordx4 v235, v[36:39], s[48:49] offset:0
	global_load_dwordx2 v[160:161], v229, s[10:11] offset:256
	s_waitcnt vmcnt(26)
	v_lshlrev_b32_e32 v136, 16, v162
	v_and_b32_e32 v137, 0xffff0000, v162
	v_lshlrev_b32_e32 v138, 16, v163
	v_and_b32_e32 v139, 0xffff0000, v163
	v_pk_add_f32 v[44:45], v[44:45], v[136:137]
	v_pk_add_f32 v[46:47], v[46:47], v[138:139]
	global_store_dwordx4 v235, v[44:47], s[48:49] offset:64
	global_load_dwordx2 v[162:163], v229, s[10:11] offset:288
	s_waitcnt vmcnt(27)
	v_lshlrev_b32_e32 v132, 16, v164
	v_and_b32_e32 v133, 0xffff0000, v164
	v_lshlrev_b32_e32 v134, 16, v165
	v_and_b32_e32 v135, 0xffff0000, v165
	v_pk_add_f32 v[80:81], v[80:81], v[132:133]
	v_pk_add_f32 v[82:83], v[82:83], v[134:135]
	global_store_dwordx4 v232, v[80:83], s[48:49] offset:512
	global_load_dwordx2 v[164:165], v230, s[10:11] offset:256
	s_waitcnt vmcnt(28)
	v_lshlrev_b32_e32 v136, 16, v166
	v_and_b32_e32 v137, 0xffff0000, v166
	v_lshlrev_b32_e32 v138, 16, v167
	v_and_b32_e32 v139, 0xffff0000, v167
	v_pk_add_f32 v[96:97], v[96:97], v[136:137]
	v_pk_add_f32 v[98:99], v[98:99], v[138:139]
	global_store_dwordx4 v232, v[96:99], s[48:49] offset:576
	global_load_dwordx2 v[166:167], v230, s[10:11] offset:288
	s_waitcnt vmcnt(29)
; DI void phaseI(int wv0, PP p, unsigned char* smem) {
;     ...
;     epi256(wv0, acc, brow, bcol, [&](int ai, int bj, int m, int n, int row, int col0, f32x4& v) {
;       const size_t o = (size_t)row * 1024 + col0;
;       const uint2 xb = *(const uint2*)(X1B + o);
;       v[0] += __uint_as_float(xb.x << 16); v[1] += __uint_as_float(xb.x & 0xffff0000u);
;       v[2] += __uint_as_float(xb.y << 16); v[3] += __uint_as_float(xb.y & 0xffff0000u);
;       *(float4*)(p->out + o) = make_float4(v[0], v[1], v[2], v[3]);
;     });
	v_lshlrev_b32_e32 v132, 16, v168
	v_and_b32_e32 v133, 0xffff0000, v168
	v_lshlrev_b32_e32 v134, 16, v169
	v_and_b32_e32 v135, 0xffff0000, v169
	v_pk_add_f32 v[84:85], v[84:85], v[132:133]
	v_pk_add_f32 v[86:87], v[86:87], v[134:135]
	global_store_dwordx4 v233, v[84:87], s[48:49] offset:512
	global_load_dwordx2 v[168:169], v231, s[10:11] offset:256
	s_waitcnt vmcnt(30)
	v_lshlrev_b32_e32 v136, 16, v170
	v_and_b32_e32 v137, 0xffff0000, v170
	v_lshlrev_b32_e32 v138, 16, v171
	v_and_b32_e32 v139, 0xffff0000, v171
	v_pk_add_f32 v[88:89], v[88:89], v[136:137]
	v_pk_add_f32 v[90:91], v[90:91], v[138:139]
	global_store_dwordx4 v233, v[88:91], s[48:49] offset:576
	global_load_dwordx2 v[170:171], v231, s[10:11] offset:288
	s_waitcnt vmcnt(31)
	v_lshlrev_b32_e32 v132, 16, v172
	v_and_b32_e32 v133, 0xffff0000, v172
	v_lshlrev_b32_e32 v134, 16, v173
	v_and_b32_e32 v135, 0xffff0000, v173
	v_pk_add_f32 v[92:93], v[92:93], v[132:133]
	v_pk_add_f32 v[94:95], v[94:95], v[134:135]
	global_store_dwordx4 v234, v[92:95], s[48:49] offset:512
	s_waitcnt vmcnt(31)
	v_lshlrev_b32_e32 v136, 16, v174
	v_and_b32_e32 v137, 0xffff0000, v174
	v_lshlrev_b32_e32 v138, 16, v175
	v_and_b32_e32 v139, 0xffff0000, v175
	v_pk_add_f32 v[112:113], v[112:113], v[136:137]
	v_pk_add_f32 v[114:115], v[114:115], v[138:139]
	global_store_dwordx4 v234, v[112:115], s[48:49] offset:576
	s_waitcnt vmcnt(31)
	v_lshlrev_b32_e32 v132, 16, v176
	v_and_b32_e32 v133, 0xffff0000, v176
	v_lshlrev_b32_e32 v134, 16, v177
	v_and_b32_e32 v135, 0xffff0000, v177
	v_pk_add_f32 v[100:101], v[100:101], v[132:133]
	v_pk_add_f32 v[102:103], v[102:103], v[134:135]
	global_store_dwordx4 v235, v[100:103], s[48:49] offset:512
	s_waitcnt vmcnt(31)
	v_lshlrev_b32_e32 v136, 16, v178
	v_and_b32_e32 v137, 0xffff0000, v178
	v_lshlrev_b32_e32 v138, 16, v179
	v_and_b32_e32 v139, 0xffff0000, v179
	v_pk_add_f32 v[108:109], v[108:109], v[136:137]
	v_pk_add_f32 v[110:111], v[110:111], v[138:139]
	global_store_dwordx4 v235, v[108:111], s[48:49] offset:576
	s_waitcnt vmcnt(31)
	v_lshlrev_b32_e32 v132, 16, v180
	v_and_b32_e32 v133, 0xffff0000, v180
	v_lshlrev_b32_e32 v134, 16, v181
	v_and_b32_e32 v135, 0xffff0000, v181
	v_pk_add_f32 v[120:121], v[120:121], v[132:133]
	v_pk_add_f32 v[122:123], v[122:123], v[134:135]
	global_store_dwordx4 v236, v[120:123], s[48:49] offset:0
	s_waitcnt vmcnt(31)
	v_lshlrev_b32_e32 v136, 16, v182
	v_and_b32_e32 v137, 0xffff0000, v182
	v_lshlrev_b32_e32 v138, 16, v183
	v_and_b32_e32 v139, 0xffff0000, v183
	v_pk_add_f32 v[124:125], v[124:125], v[136:137]
	v_pk_add_f32 v[126:127], v[126:127], v[138:139]
	global_store_dwordx4 v236, v[124:127], s[48:49] offset:64
	s_waitcnt vmcnt(31)
	v_lshlrev_b32_e32 v132, 16, v184
	v_and_b32_e32 v133, 0xffff0000, v184
	v_lshlrev_b32_e32 v134, 16, v185
	v_and_b32_e32 v135, 0xffff0000, v185
	v_pk_add_f32 v[116:117], v[116:117], v[132:133]
	v_pk_add_f32 v[118:119], v[118:119], v[134:135]
	global_store_dwordx4 v237, v[116:119], s[48:49] offset:0
	s_waitcnt vmcnt(31)
	v_lshlrev_b32_e32 v136, 16, v186
	v_and_b32_e32 v137, 0xffff0000, v186
	v_lshlrev_b32_e32 v138, 16, v187
	v_and_b32_e32 v139, 0xffff0000, v187
	v_pk_add_f32 v[104:105], v[104:105], v[136:137]
	v_pk_add_f32 v[106:107], v[106:107], v[138:139]
	global_store_dwordx4 v237, v[104:107], s[48:49] offset:64
	s_waitcnt vmcnt(30)
	v_lshlrev_b32_e32 v132, 16, v148
	v_and_b32_e32 v133, 0xffff0000, v148
	v_lshlrev_b32_e32 v134, 16, v149
	v_and_b32_e32 v135, 0xffff0000, v149
	v_pk_add_f32 v[76:77], v[76:77], v[132:133]
	v_pk_add_f32 v[78:79], v[78:79], v[134:135]
	global_store_dwordx4 v238, v[76:79], s[48:49] offset:0
	s_waitcnt vmcnt(29)
	v_lshlrev_b32_e32 v136, 16, v150
	v_and_b32_e32 v137, 0xffff0000, v150
	v_lshlrev_b32_e32 v138, 16, v151
	v_and_b32_e32 v139, 0xffff0000, v151
	v_pk_add_f32 v[72:73], v[72:73], v[136:137]
	v_pk_add_f32 v[74:75], v[74:75], v[138:139]
	global_store_dwordx4 v238, v[72:75], s[48:49] offset:64
	s_waitcnt vmcnt(28)
	v_lshlrev_b32_e32 v132, 16, v152
	v_and_b32_e32 v133, 0xffff0000, v152
	v_lshlrev_b32_e32 v134, 16, v153
	v_and_b32_e32 v135, 0xffff0000, v153
	v_pk_add_f32 v[68:69], v[68:69], v[132:133]
	v_pk_add_f32 v[70:71], v[70:71], v[134:135]
	global_store_dwordx4 v239, v[68:71], s[48:49] offset:0
	s_waitcnt vmcnt(27)
; DI void ss_partial(int wv0, f32x4 (&acc)[2][2][4][2], float* SS, int brow, int pn) {
;   const int lane = my_tid(wv0) & 63, wr = wv0 >> 2, wc = wv0 & 3;
; #pragma unroll
;   for (int ai = 0; ai < 2; ++ai)
; #pragma unroll
;     for (int m = 0; m < 4; ++m) {
;       float s = 0.f;
; #pragma unroll
;       for (int bj = 0; bj < 2; ++bj)
; #pragma unroll
;         for (int n = 0; n < 2; ++n)
; #pragma unroll
;           for (int j = 0; j < 4; ++j) s += acc[ai][bj][m][n][j] * acc[ai][bj][m][n][j];
;       s += __shfl_xor(s, 16);
;       s += __shfl_xor(s, 32);
;       if (lane < 16) SS[(size_t)(brow + ai * 128 + wr * 64 + m * 16 + lane) * 16 + pn * 4 + wc] = s;
;     }
; DI void phaseI(int wv0, PP p, unsigned char* smem) {
;     ...
;     epi256(wv0, acc, brow, bcol, [&](int ai, int bj, int m, int n, int row, int col0, f32x4& v) {
;       const size_t o = (size_t)row * 1024 + col0;
;       const uint2 xb = *(const uint2*)(X1B + o);
;       v[0] += __uint_as_float(xb.x << 16); v[1] += __uint_as_float(xb.x & 0xffff0000u);
;       v[2] += __uint_as_float(xb.y << 16); v[3] += __uint_as_float(xb.y & 0xffff0000u);
;       *(float4*)(p->out + o) = make_float4(v[0], v[1], v[2], v[3]);
;     });
;     ss_partial(wv0, acc, SS2, brow, pn);
	v_lshlrev_b32_e32 v136, 16, v154
	v_and_b32_e32 v137, 0xffff0000, v154
	v_lshlrev_b32_e32 v138, 16, v155
	v_and_b32_e32 v139, 0xffff0000, v155
	v_pk_add_f32 v[64:65], v[64:65], v[136:137]
	v_pk_add_f32 v[66:67], v[66:67], v[138:139]
	global_store_dwordx4 v239, v[64:67], s[48:49] offset:64
	s_waitcnt vmcnt(26)
	v_lshlrev_b32_e32 v132, 16, v156
	v_and_b32_e32 v133, 0xffff0000, v156
	v_lshlrev_b32_e32 v134, 16, v157
	v_and_b32_e32 v135, 0xffff0000, v157
	v_pk_add_f32 v[60:61], v[60:61], v[132:133]
	v_pk_add_f32 v[62:63], v[62:63], v[134:135]
	global_store_dwordx4 v236, v[60:63], s[48:49] offset:512
	s_waitcnt vmcnt(25)
	v_lshlrev_b32_e32 v136, 16, v158
	v_and_b32_e32 v137, 0xffff0000, v158
	v_lshlrev_b32_e32 v138, 16, v159
	v_and_b32_e32 v139, 0xffff0000, v159
	v_pk_add_f32 v[56:57], v[56:57], v[136:137]
	v_pk_add_f32 v[58:59], v[58:59], v[138:139]
	global_store_dwordx4 v236, v[56:59], s[48:49] offset:576
	s_waitcnt vmcnt(24)
	v_lshlrev_b32_e32 v132, 16, v160
	v_and_b32_e32 v133, 0xffff0000, v160
	v_lshlrev_b32_e32 v134, 16, v161
	v_and_b32_e32 v135, 0xffff0000, v161
	v_pk_add_f32 v[52:53], v[52:53], v[132:133]
	v_pk_add_f32 v[54:55], v[54:55], v[134:135]
	global_store_dwordx4 v237, v[52:55], s[48:49] offset:512
	s_waitcnt vmcnt(23)
	v_lshlrev_b32_e32 v136, 16, v162
	v_and_b32_e32 v137, 0xffff0000, v162
	v_lshlrev_b32_e32 v138, 16, v163
	v_and_b32_e32 v139, 0xffff0000, v163
	v_pk_add_f32 v[40:41], v[40:41], v[136:137]
	v_pk_add_f32 v[42:43], v[42:43], v[138:139]
	global_store_dwordx4 v237, v[40:43], s[48:49] offset:576
	s_waitcnt vmcnt(22)
	v_lshlrev_b32_e32 v132, 16, v164
	v_and_b32_e32 v133, 0xffff0000, v164
	v_lshlrev_b32_e32 v134, 16, v165
	v_and_b32_e32 v135, 0xffff0000, v165
	v_pk_add_f32 v[24:25], v[24:25], v[132:133]
	v_pk_add_f32 v[26:27], v[26:27], v[134:135]
	global_store_dwordx4 v238, v[24:27], s[48:49] offset:512
	s_waitcnt vmcnt(21)
	v_lshlrev_b32_e32 v136, 16, v166
	v_and_b32_e32 v137, 0xffff0000, v166
	v_lshlrev_b32_e32 v138, 16, v167
	v_and_b32_e32 v139, 0xffff0000, v167
	v_pk_add_f32 v[8:9], v[8:9], v[136:137]
	v_pk_add_f32 v[10:11], v[10:11], v[138:139]
	global_store_dwordx4 v238, v[8:11], s[48:49] offset:576
	s_waitcnt vmcnt(20)
	v_lshlrev_b32_e32 v132, 16, v168
	v_and_b32_e32 v133, 0xffff0000, v168
	v_lshlrev_b32_e32 v134, 16, v169
	v_and_b32_e32 v135, 0xffff0000, v169
	v_pk_add_f32 v[4:5], v[4:5], v[132:133]
	v_pk_add_f32 v[6:7], v[6:7], v[134:135]
	global_store_dwordx4 v239, v[4:7], s[48:49] offset:512
	s_waitcnt vmcnt(19)
	v_lshlrev_b32_e32 v136, 16, v170
	v_and_b32_e32 v137, 0xffff0000, v170
	v_lshlrev_b32_e32 v138, 16, v171
	v_and_b32_e32 v139, 0xffff0000, v171
	v_pk_add_f32 v[0:1], v[0:1], v[136:137]
	v_pk_add_f32 v[2:3], v[2:3], v[138:139]
	global_store_dwordx4 v239, v[0:3], s[48:49] offset:576
	v_pk_mul_f32 v[12:13], v[12:13], v[12:13]
	v_pk_mul_f32 v[14:15], v[14:15], v[14:15]
	v_add_f32_e32 v12, v12, v13
	v_add_f32_e32 v12, v12, v14
	v_pk_mul_f32 v[28:29], v[28:29], v[28:29]
	v_add_f32_e32 v12, v15, v12
	v_add_f32_e32 v12, v12, v28
	v_pk_mul_f32 v[30:31], v[30:31], v[30:31]
	v_add_f32_e32 v12, v29, v12
	v_add_f32_e32 v12, v30, v12
	v_pk_mul_f32 v[80:81], v[80:81], v[80:81]
	v_add_f32_e32 v12, v31, v12
	v_add_f32_e32 v12, v12, v80
	v_pk_mul_f32 v[82:83], v[82:83], v[82:83]
	v_add_f32_e32 v12, v81, v12
	v_add_f32_e32 v12, v82, v12
	v_pk_mul_f32 v[96:97], v[96:97], v[96:97]
	v_add_f32_e32 v12, v83, v12
	v_add_f32_e32 v12, v12, v96
	v_pk_mul_f32 v[98:99], v[98:99], v[98:99]
	v_add_f32_e32 v12, v97, v12
	v_add_f32_e32 v12, v98, v12
	v_add_f32_e32 v12, v99, v12
	ds_bpermute_b32 v13, v145, v12
	v_mov_b32_e32 v128, v144
	s_lshl_b32 s8, s68, 4
	v_and_b32_e32 v14, 63, v128
	s_waitcnt lgkmcnt(0)
	v_add_f32_e32 v13, v12, v13
	v_cmp_gt_u32_e32 vcc, 16, v14
	v_or_b32_e32 v15, s46, v14
	ds_bpermute_b32 v14, v146, v13
	s_add_u32 s46, s57, s8
	v_add_u32_e32 v12, s55, v15
	s_addc_u32 s47, s58, 0
	s_and_saveexec_b64 s[48:49], vcc
	s_cbranch_execz .LBB0_1208
	s_waitcnt lgkmcnt(0)
	v_add_f32_e32 v28, v13, v14
	v_ashrrev_i32_e32 v13, 31, v12
	v_lshlrev_b64 v[14:15], 6, v[12:13]
	v_lshl_add_u64 v[14:15], s[46:47], 0, v[14:15]
	global_store_dword v[14:15], v28, off
